# pp_v29 + first seam (P0 to P1): acquire-side buffer_inv sc1 issued right after the arrival atomic instead of after the polls
# speedup vs baseline: 1.0173x; 1.0020x over previous
.LBB0_317:
	s_or_b64 exec, exec, s[10:11]
	buffer_inv sc1
	v_cvt_f32_u32_e32 v5, v3
	s_waitcnt vmcnt(1)
	v_readfirstlane_b32 s2, v4
	v_sub_u32_e32 v4, 0, v3
	v_rcp_iflag_f32_e32 v5, v5
	v_add_u32_e32 v6, s2, v2
	v_mul_f32_e32 v5, 0x4f7ffffe, v5
	v_cvt_u32_f32_e32 v5, v5
	v_mul_lo_u32 v2, v4, v5
	v_mul_hi_u32 v2, v5, v2
	v_add_u32_e32 v2, v5, v2
	v_mul_hi_u32 v2, v6, v2
	v_mul_lo_u32 v4, v2, v3
	v_sub_u32_e32 v4, v6, v4
	v_add_u32_e32 v5, 1, v2
	v_cmp_ge_u32_e32 vcc, v4, v3
	s_nop 1
	v_cndmask_b32_e32 v2, v2, v5, vcc
	v_sub_u32_e32 v5, v4, v3
	v_cndmask_b32_e32 v4, v4, v5, vcc
	v_add_u32_e32 v5, 1, v2
	v_cmp_ge_u32_e32 vcc, v4, v3
	v_add_u32_e32 v4, 1, v6
	s_nop 0
	v_cndmask_b32_e32 v2, v2, v5, vcc
	v_mul_lo_u32 v5, v3, v2
	v_add_u32_e32 v3, v5, v3
	v_cmp_ne_u32_e32 vcc, v4, v3
	s_and_saveexec_b64 s[8:9], vcc
	s_xor_b64 s[8:9], exec, s[8:9]
	s_cbranch_execz .LBB0_331
	s_waitcnt lgkmcnt(0)
	v_mov_b32_e32 v1, 0x2000
	global_load_dword v1, v1, s[6:7] offset:1024 sc1
	s_add_u32 s14, s6, 0x2400
	s_addc_u32 s15, s7, 0
	s_waitcnt vmcnt(0)
	v_cmp_eq_u32_e32 vcc, v1, v2
	s_and_saveexec_b64 s[10:11], vcc
	s_cbranch_execz .LBB0_330
	s_add_u32 s12, s80, 0x4200
	s_addc_u32 s13, s81, 0
	s_mov_b32 s2, 1
	s_mov_b64 s[16:17], 0
	v_mov_b32_e32 v1, 0
	s_branch .LBB0_321

.LBB0_330:
	s_or_b64 exec, exec, s[10:11]
	s_waitcnt vmcnt(0)
	s_waitcnt vmcnt(0)

.LBB0_348:
	s_or_b64 exec, exec, s[8:9]
	s_mov_b64 s[8:9], exec
	v_mbcnt_lo_u32_b32 v1, s8, 0
	v_mbcnt_hi_u32_b32 v1, s9, v1
	v_cmp_eq_u32_e32 vcc, 0, v1
	s_waitcnt vmcnt(0)
	s_and_saveexec_b64 s[10:11], vcc
	s_cbranch_execz .LBB0_350
	s_bcnt1_i32_b64 s2, s[8:9]
	v_mov_b32_e32 v1, 0x2000
	v_mov_b32_e32 v2, s2
	global_atomic_add v1, v2, s[6:7] offset:1024
